# v55 + attn_prompt QK^T: K-fragment LDS reads pipelined eight ahead of the MFMAs (lever 8: LDS reads under the MFMA shadow), row addresses computed up front
# speedup vs baseline: 1.0120x; 1.0016x over previous
; #define LAS __attribute__((address_space(3)))
; __device__ __forceinline__ void attn_prompt(const Frame& F, const bf16* QKV, bf16* OG, float* LSE) {
;     ...
;                 const int hp = 128 - half;
;                 f32x4 S[10];
; #pragma unroll
;                 for (int kb = 0; kb < 9; ++kb) { const int j = 16 * w + 16 * kb + fr; const int rowk = (j < 128 ? hp : half - 128) + j;
;                     const LAS unsigned char* kp = Kl + rowk * 256; f32x4 acc = {0.f, 0.f, 0.f, 0.f};
; #pragma unroll
;                     for (int ks = 0; ks < 4; ++ks) { const bf16x8 ak = *(const LAS bf16x8*)(kp + (((4 * ks + fq) ^ fr) << 4)); acc = __builtin_amdgcn_mfma_f32_16x16x32_bf16(ak, bq[ks], acc, 0, 0, 0); }
;                     S[kb] = acc; }
.LBB0_1176:
	s_add_i32 s14, s18, s49
	v_add_u32_e32 v2, s14, v89
	s_sub_i32 s14, 0x80, s15
	s_addk_i32 s15, 0xff80
	v_mov_b32_e32 v92, s15
	v_mov_b32_e32 v93, s14
	v_xor_b32_e32 v0, v88, v89
	v_lshlrev_b32_e32 v0, 4, v0
	v_add_u32_e32 v94, 4, v88
	v_xor_b32_e32 v94, v94, v89
	v_lshlrev_b32_e32 v94, 4, v94
	v_add_u32_e32 v96, 8, v88
	v_xor_b32_e32 v96, v96, v89
	v_lshlrev_b32_e32 v96, 4, v96
	v_add_u32_e32 v97, 12, v88
	v_xor_b32_e32 v97, v97, v89
	v_lshlrev_b32_e32 v97, 4, v97
	v_or_b32_e32 v140, s18, v89
	v_cmp_gt_i32_e32 vcc, s33, v140
	s_nop 1
	v_cndmask_b32_e32 v141, v92, v93, vcc
	v_add_u32_e32 v140, v141, v140
	v_lshl_add_u32 v130, v140, 8, 0
	v_or_b32_e32 v140, s20, v89
	v_cmp_gt_i32_e32 vcc, s33, v140
	s_nop 1
	v_cndmask_b32_e32 v141, v92, v93, vcc
	v_add_u32_e32 v140, v141, v140
	v_lshl_add_u32 v131, v140, 8, 0
	v_add_u32_e32 v166, v130, v0
	ds_read_b128 v[146:149], v166
	v_add_u32_e32 v167, v130, v94
	ds_read_b128 v[150:153], v167
	v_add_u32_e32 v168, v130, v96
	ds_read_b128 v[154:157], v168
	v_add_u32_e32 v170, v130, v97
	ds_read_b128 v[158:161], v170
	v_add_u32_e32 v166, v131, v0
	ds_read_b128 v[162:165], v166
	v_add_u32_e32 v167, v131, v94
	ds_read_b128 v[196:199], v167
	v_add_u32_e32 v168, v131, v96
	ds_read_b128 v[200:203], v168
	v_add_u32_e32 v170, v131, v97
	ds_read_b128 v[204:207], v170
	v_or_b32_e32 v140, s34, v89
	v_cmp_gt_i32_e32 vcc, s33, v140
	s_nop 1
	v_cndmask_b32_e32 v141, v92, v93, vcc
	v_add_u32_e32 v140, v141, v140
	v_lshl_add_u32 v132, v140, 8, 0
	v_or_b32_e32 v140, s35, v89
	v_cmp_gt_i32_e32 vcc, s33, v140
	s_nop 1
	v_cndmask_b32_e32 v141, v92, v93, vcc
	v_add_u32_e32 v140, v141, v140
	v_lshl_add_u32 v133, v140, 8, 0
	v_or_b32_e32 v140, s40, v89
	v_cmp_gt_i32_e32 vcc, s33, v140
	s_nop 1
	v_cndmask_b32_e32 v141, v92, v93, vcc
	v_add_u32_e32 v140, v141, v140
	v_lshl_add_u32 v134, v140, 8, 0
	v_or_b32_e32 v140, s41, v89
	v_cmp_gt_i32_e32 vcc, s33, v140
	s_nop 1
	v_cndmask_b32_e32 v141, v92, v93, vcc
	v_add_u32_e32 v140, v141, v140
	v_lshl_add_u32 v135, v140, 8, 0
	v_or_b32_e32 v140, s42, v89
	v_cmp_gt_i32_e32 vcc, s33, v140
	s_nop 1
	v_cndmask_b32_e32 v141, v92, v93, vcc
	v_add_u32_e32 v140, v141, v140
	v_lshl_add_u32 v136, v140, 8, 0
	v_or_b32_e32 v140, s43, v89
	v_cmp_gt_i32_e32 vcc, s33, v140
	s_nop 1
	v_cndmask_b32_e32 v141, v92, v93, vcc
	v_add_u32_e32 v140, v141, v140
	v_lshl_add_u32 v137, v140, 8, 0
	v_or_b32_e32 v140, s19, v89
	v_cmp_gt_i32_e32 vcc, s33, v140
	s_nop 1
	v_cndmask_b32_e32 v141, v92, v93, vcc
	v_add_u32_e32 v140, v141, v140
	v_lshl_add_u32 v139, v140, 8, 0
	s_waitcnt lgkmcnt(7)
	v_mfma_f32_16x16x32_bf16 v[84:87], v[146:149], v[4:7], 0
	v_add_u32_e32 v166, v132, v0
	ds_read_b128 v[146:149], v166
	s_waitcnt lgkmcnt(7)
	v_mfma_f32_16x16x32_bf16 v[84:87], v[150:153], v[8:11], v[84:87]
	v_add_u32_e32 v167, v132, v94
	ds_read_b128 v[150:153], v167
	s_waitcnt lgkmcnt(7)
	v_mfma_f32_16x16x32_bf16 v[84:87], v[154:157], v[12:15], v[84:87]
	v_add_u32_e32 v168, v132, v96
	ds_read_b128 v[154:157], v168
	s_waitcnt lgkmcnt(7)
	v_mfma_f32_16x16x32_bf16 v[84:87], v[158:161], v[16:19], v[84:87]
	v_add_u32_e32 v170, v132, v97
	ds_read_b128 v[158:161], v170
	s_waitcnt lgkmcnt(7)
	v_mfma_f32_16x16x32_bf16 v[80:83], v[162:165], v[4:7], 0
	v_add_u32_e32 v166, v133, v0
	ds_read_b128 v[162:165], v166
	s_waitcnt lgkmcnt(7)
	v_mfma_f32_16x16x32_bf16 v[80:83], v[196:199], v[8:11], v[80:83]
	v_add_u32_e32 v167, v133, v94
	ds_read_b128 v[196:199], v167
	s_waitcnt lgkmcnt(7)
	v_mfma_f32_16x16x32_bf16 v[80:83], v[200:203], v[12:15], v[80:83]
	v_add_u32_e32 v168, v133, v96
	ds_read_b128 v[200:203], v168
	s_waitcnt lgkmcnt(7)
	v_mfma_f32_16x16x32_bf16 v[80:83], v[204:207], v[16:19], v[80:83]
	v_add_u32_e32 v170, v133, v97
	ds_read_b128 v[204:207], v170
	s_waitcnt lgkmcnt(7)
	v_mfma_f32_16x16x32_bf16 v[76:79], v[146:149], v[4:7], 0
	v_add_u32_e32 v166, v134, v0
	ds_read_b128 v[146:149], v166
	s_waitcnt lgkmcnt(7)
; #define LAS __attribute__((address_space(3)))
; #define ATT_PREFETCH_Q(qbase_, blk_) do { const bf16* qb_ = (qbase_) + (size_t)((blk_) * 128 + 16 * w + fr) * 128 + 8 * fq; \
;         _Pragma("unroll") for (int ks = 0; ks < 4; ++ks) bq[ks] = *(const bf16x8*)(qb_ + 32 * ks); } while (0)
; __device__ __forceinline__ void attn_prompt(const Frame& F, const bf16* QKV, bf16* OG, float* LSE) {
;     ...
;                 for (int kb = 0; kb < 9; ++kb) { const int j = 16 * w + 16 * kb + fr; const int rowk = (j < 128 ? hp : half - 128) + j;
;                     const LAS unsigned char* kp = Kl + rowk * 256; f32x4 acc = {0.f, 0.f, 0.f, 0.f};
; #pragma unroll
;                     for (int ks = 0; ks < 4; ++ks) { const bf16x8 ak = *(const LAS bf16x8*)(kp + (((4 * ks + fq) ^ fr) << 4)); acc = __builtin_amdgcn_mfma_f32_16x16x32_bf16(ak, bq[ks], acc, 0, 0, 0); }
;                     S[kb] = acc; }
;                 if (s + 1 < nt) ATT_PREFETCH_Q(qbase, n + 1);
	v_mfma_f32_16x16x32_bf16 v[76:79], v[150:153], v[8:11], v[76:79]
	v_add_u32_e32 v167, v134, v94
	ds_read_b128 v[150:153], v167
	s_waitcnt lgkmcnt(7)
	v_mfma_f32_16x16x32_bf16 v[76:79], v[154:157], v[12:15], v[76:79]
	v_add_u32_e32 v168, v134, v96
	ds_read_b128 v[154:157], v168
	s_waitcnt lgkmcnt(7)
	v_mfma_f32_16x16x32_bf16 v[76:79], v[158:161], v[16:19], v[76:79]
	v_add_u32_e32 v170, v134, v97
	ds_read_b128 v[158:161], v170
	s_waitcnt lgkmcnt(7)
	v_mfma_f32_16x16x32_bf16 v[72:75], v[162:165], v[4:7], 0
	v_add_u32_e32 v166, v135, v0
	ds_read_b128 v[162:165], v166
	s_waitcnt lgkmcnt(7)
	v_mfma_f32_16x16x32_bf16 v[72:75], v[196:199], v[8:11], v[72:75]
	v_add_u32_e32 v167, v135, v94
	ds_read_b128 v[196:199], v167
	s_waitcnt lgkmcnt(7)
	v_mfma_f32_16x16x32_bf16 v[72:75], v[200:203], v[12:15], v[72:75]
	v_add_u32_e32 v168, v135, v96
	ds_read_b128 v[200:203], v168
	s_waitcnt lgkmcnt(7)
	v_mfma_f32_16x16x32_bf16 v[72:75], v[204:207], v[16:19], v[72:75]
	v_add_u32_e32 v170, v135, v97
	ds_read_b128 v[204:207], v170
	s_waitcnt lgkmcnt(7)
	v_mfma_f32_16x16x32_bf16 v[68:71], v[146:149], v[4:7], 0
	v_add_u32_e32 v166, v136, v0
	ds_read_b128 v[146:149], v166
	s_waitcnt lgkmcnt(7)
	v_mfma_f32_16x16x32_bf16 v[68:71], v[150:153], v[8:11], v[68:71]
	v_add_u32_e32 v167, v136, v94
	ds_read_b128 v[150:153], v167
	s_waitcnt lgkmcnt(7)
	v_mfma_f32_16x16x32_bf16 v[68:71], v[154:157], v[12:15], v[68:71]
	v_add_u32_e32 v168, v136, v96
	ds_read_b128 v[154:157], v168
	s_waitcnt lgkmcnt(7)
	v_mfma_f32_16x16x32_bf16 v[68:71], v[158:161], v[16:19], v[68:71]
	v_add_u32_e32 v170, v136, v97
	ds_read_b128 v[158:161], v170
	s_waitcnt lgkmcnt(7)
	v_mfma_f32_16x16x32_bf16 v[64:67], v[162:165], v[4:7], 0
	v_add_u32_e32 v166, v137, v0
	ds_read_b128 v[162:165], v166
	s_waitcnt lgkmcnt(7)
	v_mfma_f32_16x16x32_bf16 v[64:67], v[196:199], v[8:11], v[64:67]
	v_add_u32_e32 v167, v137, v94
	ds_read_b128 v[196:199], v167
	s_waitcnt lgkmcnt(7)
	v_mfma_f32_16x16x32_bf16 v[64:67], v[200:203], v[12:15], v[64:67]
	v_add_u32_e32 v168, v137, v96
	ds_read_b128 v[200:203], v168
	s_waitcnt lgkmcnt(7)
	v_mfma_f32_16x16x32_bf16 v[64:67], v[204:207], v[16:19], v[64:67]
	v_add_u32_e32 v170, v137, v97
	ds_read_b128 v[204:207], v170
	s_waitcnt lgkmcnt(7)
	v_mfma_f32_16x16x32_bf16 v[60:63], v[146:149], v[4:7], 0
	v_add_u32_e32 v166, v139, v0
	ds_read_b128 v[146:149], v166
	s_waitcnt lgkmcnt(7)
	v_mfma_f32_16x16x32_bf16 v[60:63], v[150:153], v[8:11], v[60:63]
	v_add_u32_e32 v167, v139, v94
	ds_read_b128 v[150:153], v167
	s_waitcnt lgkmcnt(7)
	v_mfma_f32_16x16x32_bf16 v[60:63], v[154:157], v[12:15], v[60:63]
	v_add_u32_e32 v168, v139, v96
	ds_read_b128 v[154:157], v168
	s_waitcnt lgkmcnt(7)
	v_mfma_f32_16x16x32_bf16 v[60:63], v[158:161], v[16:19], v[60:63]
	v_add_u32_e32 v170, v139, v97
	ds_read_b128 v[158:161], v170
	s_waitcnt lgkmcnt(7)
	v_mfma_f32_16x16x32_bf16 v[56:59], v[162:165], v[4:7], 0
	s_waitcnt lgkmcnt(6)
	v_mfma_f32_16x16x32_bf16 v[56:59], v[196:199], v[8:11], v[56:59]
	s_waitcnt lgkmcnt(5)
	v_mfma_f32_16x16x32_bf16 v[56:59], v[200:203], v[12:15], v[56:59]
	s_waitcnt lgkmcnt(4)
	v_mfma_f32_16x16x32_bf16 v[56:59], v[204:207], v[16:19], v[56:59]
	s_waitcnt lgkmcnt(3)
	v_mfma_f32_16x16x32_bf16 v[52:55], v[146:149], v[4:7], 0
	s_waitcnt lgkmcnt(2)
	v_mfma_f32_16x16x32_bf16 v[52:55], v[150:153], v[8:11], v[52:55]
	s_waitcnt lgkmcnt(1)
	v_mfma_f32_16x16x32_bf16 v[52:55], v[154:157], v[12:15], v[52:55]
	s_waitcnt lgkmcnt(0)
	v_mfma_f32_16x16x32_bf16 v[52:55], v[158:161], v[16:19], v[52:55]
	s_andn2_b64 vcc, exec, s[10:11]
	s_cbranch_vccnz .LBB0_1178
	v_ashrrev_i32_e32 v3, 31, v2
	v_lshlrev_b64 v[4:5], 8, v[2:3]
	v_lshlrev_b32_e32 v6, 3, v88
	v_lshl_add_u64 v[4:5], s[24:25], 0, v[4:5]
	v_ashrrev_i32_e32 v7, 31, v6
	v_lshl_add_u64 v[16:17], v[6:7], 1, v[4:5]
	global_load_dwordx4 v[4:7], v[16:17], off
	global_load_dwordx4 v[8:11], v[16:17], off offset:64
	global_load_dwordx4 v[12:15], v[16:17], off offset:128
	s_nop 0
	global_load_dwordx4 v[16:19], v[16:17], off offset:192
